# v050_ntq
# speedup vs baseline: 1.0026x; 1.0026x over previous
.Lmy_skip_pop:
	v_mov_b32_e32 v0, s51
	s_waitcnt lgkmcnt(0)
	s_barrier
	ds_read_b32 v0, v0
	s_waitcnt lgkmcnt(0)
	v_cmp_gt_i32_e32 vcc, 0, v0
	v_readfirstlane_b32 s2, v0
	s_cbranch_vccnz .LBB0_340
	s_mul_hi_u32 s3, s2, 0xaaaaaaab
	s_lshr_b32 s3, s3, 8
	s_mul_i32 s5, s3, 0x180
	s_sub_i32 s5, s2, s5
	s_lshr_b32 s7, s5, 2
	s_and_b32 s7, s7, 0x78
	s_sub_i32 s8, s7, s3
	s_and_b32 s2, s5, 32
	s_add_i32 s8, s8, 7
	s_add_i32 s7, s7, s3
	s_cmp_eq_u32 s2, 0
	s_cselect_b32 s3, s7, s8
	s_mul_hi_i32 s7, s3, 0x2aaaaaab
	s_lshr_b32 s8, s7, 31
	s_mul_hi_i32 s21, s3, 0xd5555555
	s_add_i32 s7, s7, s8
	s_lshr_b32 s2, s21, 31
	s_mul_i32 s7, s7, 6
	s_add_i32 s21, s21, s2
	s_sub_i32 s3, s3, s7
	s_add_i32 s2, s21, 15
	s_and_b32 s5, s5, 31
	s_lshl_b32 s7, s3, 5
	s_cmp_lt_i32 s3, 4
	s_cselect_b32 s7, s7, 0
	s_lshl_b32 s8, s2, 4
	s_add_i32 s8, s8, 0
	s_add_i32 s8, s8, 0x20000
	v_mov_b32_e32 v0, s8
	s_max_i32 s3, s3, 3
	s_waitcnt vmcnt(0)
	ds_read_b96 v[2:4], v0
	s_or_b32 s22, s5, s7
	s_add_i32 s18, s3, -3
	s_cmp_eq_u32 s18, 1
	s_movk_i32 s3, 0x5000
	v_readfirstlane_b32 s9, v195
	s_cselect_b32 s25, 0x4000, s3
	s_bfe_u32 s5, s9, 0x20006
	s_lshl_b32 s10, s22, 7
	s_lshl_b32 s11, s5, 5
	s_lshr_b32 s3, s9, 6
	s_lshr_b32 s7, s9, 8
	s_or_b32 s23, s11, s10
	s_mul_i32 s12, s2, 0x600000
	s_waitcnt lgkmcnt(0)
	v_readfirstlane_b32 s8, v2
	s_mul_hi_i32 s11, s2, 0x600000
	s_add_u32 s16, s63, s12
	s_addc_u32 s17, s4, s11
	s_sub_i32 s11, s10, s8
	s_or_b32 s24, s10, 0x7f
	s_ashr_i32 s11, s11, 6
	s_add_i32 s8, s8, s24
	s_lshl_b32 s80, s7, 7
	s_add_i32 s33, s21, 16
	s_max_i32 s11, s11, 0
	s_ashr_i32 s12, s8, 6
	s_cmpk_lt_u32 s9, 0x100
	s_cselect_b64 s[8:9], -1, 0
	s_and_b64 s[14:15], s[8:9], exec
	v_readfirstlane_b32 s13, v3
	v_readfirstlane_b32 s19, v4
	s_cselect_b32 s14, 16, 32
	v_mov_b32_e32 v0, v195
	v_mov_b32_e32 v181, v194
	s_cselect_b32 s13, s13, s19
	s_add_i32 s15, s14, s2
	s_lshl_b32 s19, s5, 11
	s_cmp_eq_u32 s18, 0
	v_and_b32_e32 v0, 31, v181
	s_cselect_b32 s14, 0, s25
	v_or_b32_e32 v10, s23, v0
	v_add_u32_e32 v164, s14, v10
	v_ashrrev_i32_e32 v165, 31, v164
	v_ashrrev_i32_e32 v186, 5, v181
	v_lshlrev_b64 v[2:3], 8, v[164:165]
	v_lshl_add_u64 v[2:3], s[16:17], 0, v[2:3]
	v_lshlrev_b32_e32 v166, 3, v186
	v_lshl_add_u64 v[2:3], v[2:3], 0, s[80:81]
	v_ashrrev_i32_e32 v167, 31, v166
	v_lshl_add_u64 v[2:3], v[166:167], 1, v[2:3]
	global_load_dwordx4 v[144:147], v[2:3], off nt
	global_load_dwordx4 v[148:151], v[2:3], off offset:32 nt
	global_load_dwordx4 v[152:155], v[2:3], off offset:64 nt
	global_load_dwordx4 v[156:159], v[2:3], off offset:96 nt
	v_lshlrev_b32_e32 v3, 2, v181
	v_lshl_add_u32 v2, s7, 3, v186
	v_and_b32_e32 v3, 12, v3
	v_bfe_u32 v4, v181, 2, 2
	v_lshlrev_b32_e32 v0, 8, v0
	v_bitop3_b32 v5, v3, v2, v4 bitop3:0x36
	v_lshl_add_u32 v182, v5, 4, v0
	v_add_u32_e32 v5, 2, v2
	v_bitop3_b32 v5, v3, v5, v4 bitop3:0x36
	v_lshl_add_u32 v183, v5, 4, v0
	v_add_u32_e32 v5, 4, v2
	v_add_u32_e32 v2, 6, v2
	v_bitop3_b32 v5, v3, v5, v4 bitop3:0x36
	v_bitop3_b32 v2, v3, v2, v4 bitop3:0x36
	v_lshl_add_u32 v184, v5, 4, v0
	v_lshl_add_u32 v185, v2, 4, v0
	v_ashrrev_i32_e32 v0, 4, v181
	v_lshlrev_b32_e32 v3, 1, v0
	v_and_b32_e32 v7, 12, v181
	v_lshlrev_b32_e32 v11, 2, v186
	v_and_b32_e32 v3, 2, v3
	v_bfe_u32 v5, v181, 1, 1
	v_lshlrev_b32_e32 v8, 3, v181
	v_and_or_b32 v9, v186, 3, v7
	v_or_b32_e32 v6, v3, v5
	v_and_b32_e32 v12, 8, v8
	v_or_b32_e32 v8, v11, v4
	v_bitop3_b32 v3, v3, v9, v5 bitop3:0x36
	v_lshlrev_b32_e32 v8, 8, v8
	v_lshlrev_b32_e32 v3, 4, v3
	v_or3_b32 v187, v3, v8, v12
	v_add_u32_e32 v3, 8, v11
	v_or_b32_e32 v4, v3, v4
	v_bfe_u32 v3, v3, 2, 2
	v_lshlrev_b32_e32 v13, 8, v4
	v_bitop3_b32 v4, v3, v6, v7 bitop3:0x36
	v_lshlrev_b32_e32 v4, 4, v4
	v_or3_b32 v188, v4, v13, v12
	v_or_b32_e32 v4, 4, v6
	v_bitop3_b32 v4, v3, v4, v7 bitop3:0x36
	v_bitop3_b32 v5, v6, v9, 4 bitop3:0x36
	v_lshlrev_b32_e32 v4, 4, v4
	v_lshlrev_b32_e32 v5, 4, v5
	v_or3_b32 v190, v4, v13, v12
	v_or_b32_e32 v4, 8, v6
	v_or3_b32 v189, v5, v8, v12
	v_bitop3_b32 v5, v6, v9, 8 bitop3:0x36
	v_bitop3_b32 v4, v3, v4, v7 bitop3:0x36
	v_lshlrev_b32_e32 v5, 4, v5
	v_lshlrev_b32_e32 v4, 4, v4
	v_or3_b32 v191, v5, v8, v12
	v_or3_b32 v192, v4, v13, v12
	v_or_b32_e32 v4, 12, v6
	v_bitop3_b32 v5, v6, v9, 12 bitop3:0x36
	v_cvt_f32_i32_e32 v6, s33
	v_and_b32_e32 v2, 15, v181
	v_bitop3_b32 v14, v3, v4, v7 bitop3:0x36
	v_lshlrev_b32_e32 v5, 4, v5
	v_mul_f32_e32 v3, -0.5, v6
	v_exp_f32_e32 v15, v3
	v_lshl_add_u32 v3, v0, 7, s19
	v_lshlrev_b32_e32 v0, 5, v0
	v_lshlrev_b32_e32 v2, 3, v2
	v_or3_b32 v193, v5, v8, v12
	v_xor_b32_e32 v5, v0, v2
	v_xor_b32_e32 v2, 8, v5
	s_movk_i32 s17, 0x200
	v_add3_u32 v2, v3, v2, s17
	v_xor_b32_e32 v4, 16, v5
	s_movk_i32 s17, 0x400
	v_add_u32_e32 v0, v3, v5
	v_add3_u32 v4, v3, v4, s17
	v_xor_b32_e32 v5, 24, v5
	s_movk_i32 s17, 0x600
	v_add3_u32 v6, v3, v5, s17
	s_mul_hi_i32 s16, s15, 0x600000
	s_mul_i32 s15, s15, 0x600000
	s_cselect_b32 s17, 0xff, 63
	s_add_u32 s15, s63, s15
	s_addc_u32 s16, s4, s16
	s_lshl_b32 s14, s14, 8
	s_add_u32 s33, s15, s14
	s_addc_u32 s37, s16, 0
	s_lshr_b32 s44, s11, 1
	s_ashr_i32 s11, s10, 31
	s_lshl_b64 s[14:15], s[10:11], 8
	s_add_u32 s14, s33, s14
	s_addc_u32 s15, s37, s15
	s_lshl_b32 s11, s7, 14
	s_add_i32 s45, s11, 0
	s_lshl_b32 s11, s5, 12
	s_add_i32 s45, s45, s11
	v_lshlrev_b32_e32 v168, 1, v0
	v_lshlrev_b32_e32 v170, 1, v2
	v_lshlrev_b32_e32 v172, 1, v4
	v_lshlrev_b32_e32 v174, 1, v6
	v_mov_b32_e32 v169, v1
	v_mov_b32_e32 v171, v1
	v_mov_b32_e32 v173, v1
	v_mov_b32_e32 v175, v1
	s_mov_b32 m0, s45
	s_nop 0
	global_load_lds_dwordx4 v168, s[14:15]
	s_add_i32 m0, s45, 0x400
	s_nop 0
	global_load_lds_dwordx4 v170, s[14:15]
	s_add_i32 m0, s45, 0x800
	s_nop 0
	global_load_lds_dwordx4 v172, s[14:15]
	s_add_i32 m0, s45, 0xc00
	s_nop 0
	global_load_lds_dwordx4 v174, s[14:15]
	s_add_u32 s14, s14, 0x4000
	s_addc_u32 s15, s15, 0
	s_add_i32 m0, s45, 0x8000
	s_nop 0
	global_load_lds_dwordx4 v168, s[14:15]
	s_add_i32 m0, s45, 0x8400
	s_nop 0
	global_load_lds_dwordx4 v170, s[14:15]
	s_add_i32 m0, s45, 0x8800
	s_nop 0
	global_load_lds_dwordx4 v172, s[14:15]
	s_add_i32 m0, s45, 0x8c00
	s_nop 0
	global_load_lds_dwordx4 v174, s[14:15]
	s_waitcnt vmcnt(10)
	v_and_b32_e32 v7, 0xffff0000, v148
	v_and_b32_e32 v5, 0xffff0000, v144
	v_lshlrev_b32_e32 v3, 16, v144
	v_mul_f32_e32 v5, v5, v5
	v_fmac_f32_e32 v5, v3, v3
	v_lshlrev_b32_e32 v3, 16, v145
	v_fmac_f32_e32 v5, v3, v3
	v_and_b32_e32 v3, 0xffff0000, v145
	v_fmac_f32_e32 v5, v3, v3
	v_lshlrev_b32_e32 v3, 16, v146
	v_fmac_f32_e32 v5, v3, v3
	v_and_b32_e32 v3, 0xffff0000, v146
	v_fmac_f32_e32 v5, v3, v3
	v_lshlrev_b32_e32 v3, 16, v147
	v_fmac_f32_e32 v5, v3, v3
	v_and_b32_e32 v3, 0xffff0000, v147
	v_fmac_f32_e32 v5, v3, v3
	v_lshlrev_b32_e32 v3, 16, v148
	v_mul_f32_e32 v7, v7, v7
	v_fmac_f32_e32 v7, v3, v3
	v_lshlrev_b32_e32 v3, 16, v149
	v_fmac_f32_e32 v7, v3, v3
	v_and_b32_e32 v3, 0xffff0000, v149
	v_fmac_f32_e32 v7, v3, v3
	v_lshlrev_b32_e32 v3, 16, v150
	v_fmac_f32_e32 v7, v3, v3
	v_and_b32_e32 v3, 0xffff0000, v150
	v_fmac_f32_e32 v7, v3, v3
	v_lshlrev_b32_e32 v3, 16, v151
	v_fmac_f32_e32 v7, v3, v3
	v_and_b32_e32 v3, 0xffff0000, v151
	v_fmac_f32_e32 v7, v3, v3
	v_add_f32_e32 v3, v5, v7
	s_waitcnt vmcnt(9)
	v_and_b32_e32 v7, 0xffff0000, v152
	v_lshlrev_b32_e32 v5, 16, v152
	v_mul_f32_e32 v7, v7, v7
	v_fmac_f32_e32 v7, v5, v5
	v_lshlrev_b32_e32 v5, 16, v153
	v_fmac_f32_e32 v7, v5, v5
	v_and_b32_e32 v5, 0xffff0000, v153
	v_fmac_f32_e32 v7, v5, v5
	v_lshlrev_b32_e32 v5, 16, v154
	v_fmac_f32_e32 v7, v5, v5
	v_and_b32_e32 v5, 0xffff0000, v154
	v_fmac_f32_e32 v7, v5, v5
	v_lshlrev_b32_e32 v5, 16, v155
	v_fmac_f32_e32 v7, v5, v5
	v_and_b32_e32 v5, 0xffff0000, v155
	v_fmac_f32_e32 v7, v5, v5
	s_waitcnt vmcnt(8)
	v_and_b32_e32 v5, 0xffff0000, v156
	v_add_f32_e32 v16, v3, v7
	v_lshlrev_b32_e32 v3, 16, v156
	v_mul_f32_e32 v17, v5, v5
	v_fmac_f32_e32 v17, v3, v3
	v_lshlrev_b32_e32 v3, 16, v157
	v_fmac_f32_e32 v17, v3, v3
	v_and_b32_e32 v3, 0xffff0000, v157
	v_fmac_f32_e32 v17, v3, v3
	v_lshlrev_b32_e32 v3, 16, v158
	v_fmac_f32_e32 v17, v3, v3
	v_mov_b32_e32 v3, v1
	v_mov_b32_e32 v5, v1
	v_mov_b32_e32 v7, v1
	v_and_b32_e32 v0, 0xffff0000, v158
	v_fmac_f32_e32 v17, v0, v0
	v_lshlrev_b32_e32 v0, 16, v159
	v_fmac_f32_e32 v17, v0, v0
	v_and_b32_e32 v0, 0xffff0000, v159
	v_fmac_f32_e32 v17, v0, v0
	v_add_f32_e32 v0, v16, v17
	v_mov_b32_e32 v2, v0
	s_nop 1
	v_permlane32_swap_b32_e32 v0, v2
	v_add_f32_e32 v0, v0, v2
	v_mul_f32_e32 v2, 0x4f800000, v0
	v_cmp_gt_f32_e32 vcc, s65, v0
	v_lshlrev_b32_e32 v3, 4, v14
	v_or3_b32 v196, v3, v13, v12
	v_cndmask_b32_e32 v0, v0, v2, vcc
	v_sqrt_f32_e32 v2, v0
	s_min_i32 s11, s17, s12
	s_ashr_i32 s46, s11, 1
	s_lshl_b32 s11, s3, 2
	v_add_u32_e32 v3, -1, v2
	v_fma_f32 v4, -v3, v2, v0
	v_cmp_ge_f32_e64 s[38:39], 0, v4
	v_add_u32_e32 v4, 1, v2
	s_add_i32 s48, s11, 0
	v_cndmask_b32_e64 v3, v2, v3, s[38:39]
	v_fma_f32 v2, -v4, v2, v0
	v_cmp_lt_f32_e64 s[38:39], 0, v2
	s_or_b32 s47, s23, 31
	s_add_i32 s48, s48, 0x20440
	v_cndmask_b32_e64 v2, v3, v4, s[38:39]
	v_mul_f32_e32 v3, 0x37800000, v2
	v_cndmask_b32_e32 v2, v2, v3, vcc
	v_cmp_class_f32_e32 vcc, v0, v227
	s_add_i32 s49, s22, 1
	s_cmp_lt_i32 s22, s46
	v_cndmask_b32_e32 v0, v2, v0, vcc
	v_mul_f32_e32 v176, 0x3fb8aa3b, v15
	v_mul_f32_e32 v0, 0x3e3a82f9, v0
	s_cselect_b32 s11, s49, -1
	s_add_i32 s12, s22, -1
	s_or_b32 s50, s10, 1
	v_mov_b32_e32 v14, v1
	v_mov_b32_e32 v15, v1
	v_mul_f32_e32 v197, s13, v0
	v_sub_u32_e32 v198, v11, v10
	v_xor_b32_e32 v178, 0x80000000, v176
	s_cmp_gt_i32 s22, s44
	v_mov_b32_e32 v0, v1
	v_mov_b32_e32 v2, v1
	v_mov_b32_e32 v3, v1
	v_mov_b32_e32 v4, v1
	v_mov_b32_e32 v6, v1
	v_mov_b32_e32 v8, v1
	v_mov_b32_e32 v9, v1
	v_mov_b32_e32 v10, v1
	v_mov_b32_e32 v11, v1
	v_mov_b32_e32 v12, v1
	v_mov_b32_e32 v13, v1
	v_mov_b64_e32 v[30:31], v[14:15]
	v_mov_b64_e32 v[46:47], v[14:15]
	v_mov_b64_e32 v[62:63], v[14:15]
	v_mov_b64_e32 v[78:79], v[14:15]
	s_mov_b32 s25, 0
	v_cmp_eq_u32_e64 s[38:39], 0, v181
	s_cselect_b32 s79, s12, s11
	s_cselect_b32 s78, 1, 2
	v_mov_b32_e32 v177, v176
	v_mov_b32_e32 v179, v178
	v_mul_f32_e32 v201, 0xc27c0000, v176
	v_add_f32_e32 v201, 0x41000000, v201
	s_nop 0
	v_readfirstlane_b32 s100, v201
	v_mov_b32_e32 v201, 0
	v_mov_b32_e32 v199, 0
	s_mov_b32 s83, 0
	v_mov_b32_e32 v180, 0
	v_mov_b64_e32 v[28:29], v[12:13]
	v_mov_b64_e32 v[26:27], v[10:11]
	v_mov_b64_e32 v[24:25], v[8:9]
	v_mov_b64_e32 v[22:23], v[6:7]
	v_mov_b64_e32 v[20:21], v[4:5]
	v_mov_b64_e32 v[18:19], v[2:3]
	v_mov_b64_e32 v[16:17], v[0:1]
	v_mov_b64_e32 v[44:45], v[12:13]
	v_mov_b64_e32 v[42:43], v[10:11]
	v_mov_b64_e32 v[40:41], v[8:9]
	v_mov_b64_e32 v[38:39], v[6:7]
	v_mov_b64_e32 v[36:37], v[4:5]
	v_mov_b64_e32 v[34:35], v[2:3]
	v_mov_b64_e32 v[32:33], v[0:1]
	v_mov_b64_e32 v[60:61], v[12:13]
	v_mov_b64_e32 v[58:59], v[10:11]
	v_mov_b64_e32 v[56:57], v[8:9]
	v_mov_b64_e32 v[54:55], v[6:7]
	v_mov_b64_e32 v[52:53], v[4:5]
	v_mov_b64_e32 v[50:51], v[2:3]
	v_mov_b64_e32 v[48:49], v[0:1]
	v_mov_b64_e32 v[76:77], v[12:13]
	v_mov_b64_e32 v[74:75], v[10:11]
	v_mov_b64_e32 v[72:73], v[8:9]
	v_mov_b64_e32 v[70:71], v[6:7]
	v_mov_b64_e32 v[68:69], v[4:5]
	v_mov_b64_e32 v[66:67], v[2:3]
	v_mov_b64_e32 v[64:65], v[0:1]
	s_mov_b32 s18, s22
	s_mov_b32 s10, 0
	v_readfirstlane_b32 s101, v195
	s_cmpk_lt_u32 s101, 0x100
	s_cbranch_scc1 .Lmy_prio_lo
	s_setprio 1

.LBB0_334:
	s_setprio 0
	v_cndmask_b32_e64 v0, 0, 1, s[8:9]
	v_cmp_ne_u32_e64 s[38:39], 1, v0
	s_andn2_b64 vcc, exec, s[8:9]
	s_cbranch_vccnz .LBB0_336
	s_add_i32 s8, s21, 63
	s_mul_hi_i32 s9, s8, 0x600000
	s_mul_i32 s8, s8, 0x600000
	s_add_u32 s8, s63, s8
	s_addc_u32 s9, s4, s9
	v_lshlrev_b64 v[2:3], 7, v[164:165]
	v_lshl_add_u64 v[2:3], v[2:3], 1, s[8:9]
	v_lshl_add_u64 v[2:3], v[166:167], 1, v[2:3]
	global_load_dwordx4 v[104:107], v[2:3], off nt
	global_load_dwordx4 v[100:103], v[2:3], off offset:32 nt
	global_load_dwordx4 v[96:99], v[2:3], off offset:64 nt
	global_load_dwordx4 v[92:95], v[2:3], off offset:96 nt
	global_load_dwordx4 v[88:91], v[2:3], off offset:128 nt
	global_load_dwordx4 v[10:13], v[2:3], off offset:160 nt
	global_load_dwordx4 v[6:9], v[2:3], off offset:192 nt
	s_nop 0
	global_load_dwordx4 v[2:5], v[2:3], off offset:224 nt
